# GEMM K-loop back-edge bookkeeping (pointer bumps + counter compare) moved above the closing barrier
# baseline (speedup 1.0000x reference)
.LBB0_153:
	s_add_u32 s36, s22, 0xfffc0080
	s_addc_u32 s37, s23, -1
	s_add_i32 s43, 0, 0x10000
	s_cmp_eq_u32 s42, 12
	s_cselect_b32 s41, s3, s37
	s_cselect_b32 s40, s21, s36
	v_add_u32_e32 v148, s43, v150
	s_cselect_b32 s37, s26, s35
	s_cselect_b32 s36, s33, s34
	s_add_i32 s47, 0, 0x14000
	ds_read_b128 v[140:143], v148
	ds_read_b128 v[144:147], v148 offset:1024
	ds_read_b128 v[152:155], v148 offset:2048
	ds_read_b128 v[156:159], v148 offset:3072
	v_add_u32_e32 v148, s47, v150
	ds_read_b128 v[160:163], v148
	ds_read_b128 v[164:167], v148 offset:1024
	ds_read_b128 v[168:171], v148 offset:2048
	ds_read_b128 v[172:175], v148 offset:3072
	v_lshl_add_u64 v[148:149], s[22:23], 0, v[136:137]
	s_add_i32 m0, s63, 0xc000
	ds_read_b128 v[194:197], v133
	ds_read_b128 v[198:201], v133 offset:1024
	ds_read_b128 v[202:205], v133 offset:2048
	ds_read_b128 v[206:209], v133 offset:3072
	ds_read_b128 v[210:213], v133 offset:4096
	ds_read_b128 v[226:229], v133 offset:5120
	ds_read_b128 v[230:233], v133 offset:6144
	ds_read_b128 v[234:237], v133 offset:7168
	global_load_lds_dwordx4 v[148:149], off
	v_lshl_add_u64 v[148:149], s[22:23], 0, v[138:139]
	s_add_i32 m0, s63, 0xe000
	s_nop 0
	global_load_lds_dwordx4 v[148:149], off
	s_waitcnt vmcnt(8)
	s_waitcnt lgkmcnt(0)
	s_barrier
	s_setprio 1
	s_waitcnt lgkmcnt(0)
	v_mfma_f32_16x16x32_bf16 v[124:127], v[140:143], v[194:197], v[124:127]
	v_mfma_f32_16x16x32_bf16 v[120:123], v[152:155], v[194:197], v[120:123]
	v_mfma_f32_16x16x32_bf16 v[108:111], v[140:143], v[202:205], v[108:111]
	v_mfma_f32_16x16x32_bf16 v[104:107], v[152:155], v[202:205], v[104:107]
	v_mfma_f32_16x16x32_bf16 v[92:95], v[140:143], v[210:213], v[92:95]
	v_mfma_f32_16x16x32_bf16 v[88:91], v[152:155], v[210:213], v[88:91]
	v_mfma_f32_16x16x32_bf16 v[76:79], v[140:143], v[230:233], v[76:79]
	v_mfma_f32_16x16x32_bf16 v[72:75], v[152:155], v[230:233], v[72:75]
	v_mfma_f32_16x16x32_bf16 v[124:127], v[144:147], v[198:201], v[124:127]
	v_mfma_f32_16x16x32_bf16 v[120:123], v[156:159], v[198:201], v[120:123]
	v_mfma_f32_16x16x32_bf16 v[108:111], v[144:147], v[206:209], v[108:111]
	v_mfma_f32_16x16x32_bf16 v[104:107], v[156:159], v[206:209], v[104:107]
	v_mfma_f32_16x16x32_bf16 v[92:95], v[144:147], v[226:229], v[92:95]
	v_mfma_f32_16x16x32_bf16 v[88:91], v[156:159], v[226:229], v[88:91]
	v_mfma_f32_16x16x32_bf16 v[76:79], v[144:147], v[234:237], v[76:79]
	v_mfma_f32_16x16x32_bf16 v[72:75], v[156:159], v[234:237], v[72:75]
	s_setprio 0
	s_setprio 1
	v_mfma_f32_16x16x32_bf16 v[116:119], v[160:163], v[194:197], v[116:119]
	v_mfma_f32_16x16x32_bf16 v[112:115], v[168:171], v[194:197], v[112:115]
	v_mfma_f32_16x16x32_bf16 v[100:103], v[160:163], v[202:205], v[100:103]
	v_mfma_f32_16x16x32_bf16 v[96:99], v[168:171], v[202:205], v[96:99]
	v_mfma_f32_16x16x32_bf16 v[84:87], v[160:163], v[210:213], v[84:87]
	v_mfma_f32_16x16x32_bf16 v[80:83], v[168:171], v[210:213], v[80:83]
	v_mfma_f32_16x16x32_bf16 v[68:71], v[160:163], v[230:233], v[68:71]
	v_mfma_f32_16x16x32_bf16 v[64:67], v[168:171], v[230:233], v[64:67]
	v_mfma_f32_16x16x32_bf16 v[116:119], v[164:167], v[198:201], v[116:119]
	v_mfma_f32_16x16x32_bf16 v[112:115], v[172:175], v[198:201], v[112:115]
	v_mfma_f32_16x16x32_bf16 v[100:103], v[164:167], v[206:209], v[100:103]
	v_mfma_f32_16x16x32_bf16 v[96:99], v[172:175], v[206:209], v[96:99]
	v_mfma_f32_16x16x32_bf16 v[84:87], v[164:167], v[226:229], v[84:87]
	v_mfma_f32_16x16x32_bf16 v[80:83], v[172:175], v[226:229], v[80:83]
	v_mfma_f32_16x16x32_bf16 v[68:71], v[164:167], v[234:237], v[68:71]
	v_mfma_f32_16x16x32_bf16 v[64:67], v[172:175], v[234:237], v[64:67]
	s_setprio 0
	s_barrier
	s_add_i32 s43, s43, s62
	v_lshl_add_u64 v[148:149], s[36:37], 0, v[128:129]
	s_mov_b32 m0, s43
	ds_read_b128 v[194:197], v133 offset:16384
	ds_read_b128 v[198:201], v133 offset:17408
	ds_read_b128 v[202:205], v133 offset:18432
	ds_read_b128 v[206:209], v133 offset:19456
	ds_read_b128 v[210:213], v133 offset:20480
	ds_read_b128 v[226:229], v133 offset:21504
	ds_read_b128 v[230:233], v133 offset:22528
	ds_read_b128 v[234:237], v133 offset:23552
	global_load_lds_dwordx4 v[148:149], off
	s_add_i32 m0, s43, 0x2000
	s_add_u32 s56, s36, 0x40000
	v_lshl_add_u64 v[176:177], s[36:37], 0, v[130:131]
	s_addc_u32 s57, s37, 0
	s_add_i32 s43, s47, s62
	global_load_lds_dwordx4 v[176:177], off
	v_lshl_add_u64 v[184:185], s[56:57], 0, v[128:129]
	s_mov_b32 m0, s43
	v_lshl_add_u64 v[238:239], s[40:41], 0, v[130:131]
	global_load_lds_dwordx4 v[184:185], off
	v_lshl_add_u64 v[184:185], s[56:57], 0, v[130:131]
	s_add_i32 m0, s43, 0x2000
	s_nop 0
	global_load_lds_dwordx4 v[184:185], off
	v_lshl_add_u64 v[184:185], s[40:41], 0, v[128:129]
	s_mov_b32 m0, s63
	s_nop 0
	global_load_lds_dwordx4 v[184:185], off
	s_mov_b32 m0, s80
	s_nop 0
	global_load_lds_dwordx4 v[238:239], off
	s_waitcnt vmcnt(8)
	s_waitcnt lgkmcnt(0)
	s_barrier
	s_setprio 1
	s_waitcnt lgkmcnt(0)
	v_mfma_f32_16x16x32_bf16 v[60:63], v[140:143], v[194:197], v[60:63]
	v_mfma_f32_16x16x32_bf16 v[56:59], v[152:155], v[194:197], v[56:59]
	v_mfma_f32_16x16x32_bf16 v[44:47], v[140:143], v[202:205], v[44:47]
	v_mfma_f32_16x16x32_bf16 v[40:43], v[152:155], v[202:205], v[40:43]
	v_mfma_f32_16x16x32_bf16 v[28:31], v[140:143], v[210:213], v[28:31]
	v_mfma_f32_16x16x32_bf16 v[24:27], v[152:155], v[210:213], v[24:27]
	v_mfma_f32_16x16x32_bf16 v[12:15], v[140:143], v[230:233], v[12:15]
	v_mfma_f32_16x16x32_bf16 v[8:11], v[152:155], v[230:233], v[8:11]
	v_mfma_f32_16x16x32_bf16 v[60:63], v[144:147], v[198:201], v[60:63]
	v_mfma_f32_16x16x32_bf16 v[56:59], v[156:159], v[198:201], v[56:59]
	v_mfma_f32_16x16x32_bf16 v[44:47], v[144:147], v[206:209], v[44:47]
	v_mfma_f32_16x16x32_bf16 v[40:43], v[156:159], v[206:209], v[40:43]
	v_mfma_f32_16x16x32_bf16 v[28:31], v[144:147], v[226:229], v[28:31]
	v_mfma_f32_16x16x32_bf16 v[24:27], v[156:159], v[226:229], v[24:27]
	v_mfma_f32_16x16x32_bf16 v[12:15], v[144:147], v[234:237], v[12:15]
	v_mfma_f32_16x16x32_bf16 v[8:11], v[156:159], v[234:237], v[8:11]
	s_setprio 0
	s_setprio 1
	v_mfma_f32_16x16x32_bf16 v[52:55], v[160:163], v[194:197], v[52:55]
	v_mfma_f32_16x16x32_bf16 v[48:51], v[168:171], v[194:197], v[48:51]
	v_mfma_f32_16x16x32_bf16 v[36:39], v[160:163], v[202:205], v[36:39]
	v_mfma_f32_16x16x32_bf16 v[32:35], v[168:171], v[202:205], v[32:35]
	v_mfma_f32_16x16x32_bf16 v[20:23], v[160:163], v[210:213], v[20:23]
	v_mfma_f32_16x16x32_bf16 v[16:19], v[168:171], v[210:213], v[16:19]
	v_mfma_f32_16x16x32_bf16 v[4:7], v[160:163], v[230:233], v[4:7]
	v_mfma_f32_16x16x32_bf16 v[0:3], v[168:171], v[230:233], v[0:3]
	v_mfma_f32_16x16x32_bf16 v[52:55], v[164:167], v[198:201], v[52:55]
	v_mfma_f32_16x16x32_bf16 v[48:51], v[172:175], v[198:201], v[48:51]
	v_mfma_f32_16x16x32_bf16 v[36:39], v[164:167], v[206:209], v[36:39]
	v_mfma_f32_16x16x32_bf16 v[32:35], v[172:175], v[206:209], v[32:35]
	v_mfma_f32_16x16x32_bf16 v[20:23], v[164:167], v[226:229], v[20:23]
	v_mfma_f32_16x16x32_bf16 v[16:19], v[172:175], v[226:229], v[16:19]
	v_mfma_f32_16x16x32_bf16 v[4:7], v[164:167], v[234:237], v[4:7]
	v_mfma_f32_16x16x32_bf16 v[0:3], v[172:175], v[234:237], v[0:3]
	s_setprio 0
	s_barrier
	s_add_i32 s43, 0, 0x18000
	s_add_i32 s47, 0, 0x1c000
	v_add_u32_e32 v156, s43, v150
	v_add_u32_e32 v172, s47, v150
	ds_read_b128 v[140:143], v156
	ds_read_b128 v[144:147], v156 offset:1024
	ds_read_b128 v[152:155], v156 offset:2048
	ds_read_b128 v[156:159], v156 offset:3072
	ds_read_b128 v[160:163], v172
	ds_read_b128 v[164:167], v172 offset:1024
	ds_read_b128 v[168:171], v172 offset:2048
	ds_read_b128 v[172:175], v172 offset:3072
	s_add_u32 s40, s40, 0x40000
	s_addc_u32 s41, s41, 0
	s_mov_b32 m0, s81
	v_lshl_add_u64 v[240:241], s[40:41], 0, v[128:129]
	ds_read_b128 v[194:197], v133 offset:32768
	ds_read_b128 v[198:201], v133 offset:33792
	ds_read_b128 v[202:205], v133 offset:34816
	ds_read_b128 v[206:209], v133 offset:35840
	ds_read_b128 v[210:213], v133 offset:36864
	ds_read_b128 v[226:229], v133 offset:37888
	ds_read_b128 v[230:233], v133 offset:38912
	ds_read_b128 v[234:237], v133 offset:39936
	global_load_lds_dwordx4 v[240:241], off
	v_lshl_add_u64 v[240:241], s[40:41], 0, v[130:131]
	s_mov_b32 m0, s82
	s_nop 0
	global_load_lds_dwordx4 v[240:241], off
	s_waitcnt vmcnt(8)
	s_waitcnt lgkmcnt(0)
	s_barrier
	s_setprio 1
	s_waitcnt lgkmcnt(0)
	v_mfma_f32_16x16x32_bf16 v[124:127], v[140:143], v[194:197], v[124:127]
	v_mfma_f32_16x16x32_bf16 v[120:123], v[152:155], v[194:197], v[120:123]
	v_mfma_f32_16x16x32_bf16 v[108:111], v[140:143], v[202:205], v[108:111]
	v_mfma_f32_16x16x32_bf16 v[104:107], v[152:155], v[202:205], v[104:107]
	v_mfma_f32_16x16x32_bf16 v[92:95], v[140:143], v[210:213], v[92:95]
	v_mfma_f32_16x16x32_bf16 v[88:91], v[152:155], v[210:213], v[88:91]
	v_mfma_f32_16x16x32_bf16 v[76:79], v[140:143], v[230:233], v[76:79]
	v_mfma_f32_16x16x32_bf16 v[72:75], v[152:155], v[230:233], v[72:75]
	v_mfma_f32_16x16x32_bf16 v[124:127], v[144:147], v[198:201], v[124:127]
	v_mfma_f32_16x16x32_bf16 v[120:123], v[156:159], v[198:201], v[120:123]
	v_mfma_f32_16x16x32_bf16 v[108:111], v[144:147], v[206:209], v[108:111]
	v_mfma_f32_16x16x32_bf16 v[104:107], v[156:159], v[206:209], v[104:107]
	v_mfma_f32_16x16x32_bf16 v[92:95], v[144:147], v[226:229], v[92:95]
	v_mfma_f32_16x16x32_bf16 v[88:91], v[156:159], v[226:229], v[88:91]
	v_mfma_f32_16x16x32_bf16 v[76:79], v[144:147], v[234:237], v[76:79]
	v_mfma_f32_16x16x32_bf16 v[72:75], v[156:159], v[234:237], v[72:75]
	s_setprio 0
	s_setprio 1
	v_mfma_f32_16x16x32_bf16 v[116:119], v[160:163], v[194:197], v[116:119]
	v_mfma_f32_16x16x32_bf16 v[112:115], v[168:171], v[194:197], v[112:115]
	v_mfma_f32_16x16x32_bf16 v[100:103], v[160:163], v[202:205], v[100:103]
	v_mfma_f32_16x16x32_bf16 v[96:99], v[168:171], v[202:205], v[96:99]
	v_mfma_f32_16x16x32_bf16 v[84:87], v[160:163], v[210:213], v[84:87]
	v_mfma_f32_16x16x32_bf16 v[80:83], v[168:171], v[210:213], v[80:83]
	v_mfma_f32_16x16x32_bf16 v[68:71], v[160:163], v[230:233], v[68:71]
	v_mfma_f32_16x16x32_bf16 v[64:67], v[168:171], v[230:233], v[64:67]
	v_mfma_f32_16x16x32_bf16 v[116:119], v[164:167], v[198:201], v[116:119]
	v_mfma_f32_16x16x32_bf16 v[112:115], v[172:175], v[198:201], v[112:115]
	v_mfma_f32_16x16x32_bf16 v[100:103], v[164:167], v[206:209], v[100:103]
	v_mfma_f32_16x16x32_bf16 v[96:99], v[172:175], v[206:209], v[96:99]
	v_mfma_f32_16x16x32_bf16 v[84:87], v[164:167], v[226:229], v[84:87]
	v_mfma_f32_16x16x32_bf16 v[80:83], v[172:175], v[226:229], v[80:83]
	v_mfma_f32_16x16x32_bf16 v[68:71], v[164:167], v[234:237], v[68:71]
	v_mfma_f32_16x16x32_bf16 v[64:67], v[172:175], v[234:237], v[64:67]
	s_setprio 0
	s_barrier
	s_add_i32 s40, s43, s62
	v_lshl_add_u64 v[148:149], v[148:149], 0, s[28:29]
	s_mov_b32 m0, s40
	ds_read_b128 v[194:197], v133 offset:49152
	ds_read_b128 v[198:201], v133 offset:50176
	ds_read_b128 v[202:205], v133 offset:51200
	ds_read_b128 v[206:209], v133 offset:52224
	ds_read_b128 v[210:213], v133 offset:53248
	ds_read_b128 v[226:229], v133 offset:54272
	ds_read_b128 v[230:233], v133 offset:55296
	ds_read_b128 v[234:237], v133 offset:56320
	global_load_lds_dwordx4 v[148:149], off
	s_add_i32 m0, s40, 0x2000
	s_add_u32 s36, s36, 0x40080
	v_lshl_add_u64 v[148:149], v[176:177], 0, s[28:29]
	s_addc_u32 s37, s37, 0
	s_add_i32 s40, s47, s62
	global_load_lds_dwordx4 v[148:149], off
	v_lshl_add_u64 v[148:149], s[36:37], 0, v[128:129]
	s_mov_b32 m0, s40
	s_nop 0
	global_load_lds_dwordx4 v[148:149], off
	v_lshl_add_u64 v[148:149], s[36:37], 0, v[130:131]
	s_add_i32 m0, s40, 0x2000
	s_nop 0
	global_load_lds_dwordx4 v[148:149], off
	v_lshl_add_u64 v[148:149], v[184:185], 0, s[28:29]
	s_mov_b32 m0, s84
	s_nop 0
	global_load_lds_dwordx4 v[148:149], off
	v_lshl_add_u64 v[148:149], v[238:239], 0, s[28:29]
	s_mov_b32 m0, s85
	s_nop 0
	global_load_lds_dwordx4 v[148:149], off
	s_waitcnt vmcnt(8)
	s_waitcnt lgkmcnt(0)
	s_barrier
	s_setprio 1
	s_waitcnt lgkmcnt(0)
	v_mfma_f32_16x16x32_bf16 v[60:63], v[140:143], v[194:197], v[60:63]
	v_mfma_f32_16x16x32_bf16 v[56:59], v[152:155], v[194:197], v[56:59]
	v_mfma_f32_16x16x32_bf16 v[44:47], v[140:143], v[202:205], v[44:47]
	v_mfma_f32_16x16x32_bf16 v[40:43], v[152:155], v[202:205], v[40:43]
	v_mfma_f32_16x16x32_bf16 v[28:31], v[140:143], v[210:213], v[28:31]
	v_mfma_f32_16x16x32_bf16 v[24:27], v[152:155], v[210:213], v[24:27]
	v_mfma_f32_16x16x32_bf16 v[12:15], v[140:143], v[230:233], v[12:15]
	v_mfma_f32_16x16x32_bf16 v[8:11], v[152:155], v[230:233], v[8:11]
	v_mfma_f32_16x16x32_bf16 v[60:63], v[144:147], v[198:201], v[60:63]
	v_mfma_f32_16x16x32_bf16 v[56:59], v[156:159], v[198:201], v[56:59]
	v_mfma_f32_16x16x32_bf16 v[44:47], v[144:147], v[206:209], v[44:47]
	v_mfma_f32_16x16x32_bf16 v[40:43], v[156:159], v[206:209], v[40:43]
	v_mfma_f32_16x16x32_bf16 v[28:31], v[144:147], v[226:229], v[28:31]
	v_mfma_f32_16x16x32_bf16 v[24:27], v[156:159], v[226:229], v[24:27]
	v_mfma_f32_16x16x32_bf16 v[12:15], v[144:147], v[234:237], v[12:15]
	v_mfma_f32_16x16x32_bf16 v[8:11], v[156:159], v[234:237], v[8:11]
	s_setprio 0
	s_setprio 1
	v_mfma_f32_16x16x32_bf16 v[52:55], v[160:163], v[194:197], v[52:55]
	v_mfma_f32_16x16x32_bf16 v[48:51], v[168:171], v[194:197], v[48:51]
	v_mfma_f32_16x16x32_bf16 v[36:39], v[160:163], v[202:205], v[36:39]
	v_mfma_f32_16x16x32_bf16 v[32:35], v[168:171], v[202:205], v[32:35]
	v_mfma_f32_16x16x32_bf16 v[20:23], v[160:163], v[210:213], v[20:23]
	v_mfma_f32_16x16x32_bf16 v[16:19], v[168:171], v[210:213], v[16:19]
	v_mfma_f32_16x16x32_bf16 v[4:7], v[160:163], v[230:233], v[4:7]
	v_mfma_f32_16x16x32_bf16 v[0:3], v[168:171], v[230:233], v[0:3]
	v_mfma_f32_16x16x32_bf16 v[52:55], v[164:167], v[198:201], v[52:55]
	v_mfma_f32_16x16x32_bf16 v[48:51], v[172:175], v[198:201], v[48:51]
	v_mfma_f32_16x16x32_bf16 v[36:39], v[164:167], v[206:209], v[36:39]
	v_mfma_f32_16x16x32_bf16 v[32:35], v[172:175], v[206:209], v[32:35]
	v_mfma_f32_16x16x32_bf16 v[20:23], v[164:167], v[226:229], v[20:23]
	v_mfma_f32_16x16x32_bf16 v[16:19], v[172:175], v[226:229], v[16:19]
	v_mfma_f32_16x16x32_bf16 v[4:7], v[164:167], v[234:237], v[4:7]
	v_mfma_f32_16x16x32_bf16 v[0:3], v[172:175], v[234:237], v[0:3]
	s_setprio 0
	s_add_i32 s42, s42, 2
	s_add_u32 s22, s22, 0x100
	s_addc_u32 s23, s23, 0
	s_add_u32 s34, s34, 0x100
	s_addc_u32 s35, s35, 0
	s_cmp_gt_u32 s42, 13
	s_barrier
	s_cbranch_scc0 .LBB0_153
	s_and_b64 vcc, exec, s[44:45]
	s_cbranch_vccz .LBB0_156
	s_barrier

.LBB0_628:
	s_add_u32 s40, s44, 0xfffc0080
	s_addc_u32 s41, s45, -1
	s_add_i32 s91, 0, 0x10000
	s_cmp_eq_u32 s39, 12
	s_cselect_b32 vcc_hi, s1, s41
	s_cselect_b32 vcc_lo, s2, s40
	s_cselect_b32 s63, s3, s38
	s_cselect_b32 s62, s21, s37
	s_add_i32 s54, 0, 0x14000
	v_add_u32_e32 v72, s91, v210
	v_add_u32_e32 v92, s54, v210
	ds_read_b128 v[60:63], v72
	ds_read_b128 v[64:67], v72 offset:1024
	ds_read_b128 v[68:71], v72 offset:2048
	ds_read_b128 v[72:75], v72 offset:3072
	ds_read_b128 v[80:83], v92
	ds_read_b128 v[84:87], v92 offset:1024
	ds_read_b128 v[88:91], v92 offset:2048
	ds_read_b128 v[92:95], v92 offset:3072
	v_lshl_add_u64 v[96:97], s[44:45], 0, v[204:205]
	s_add_i32 m0, s35, 0xc000
	ds_read_b128 v[158:161], v230
	ds_read_b128 v[162:165], v230 offset:1024
	ds_read_b128 v[170:173], v230 offset:2048
	ds_read_b128 v[174:177], v230 offset:3072
	ds_read_b128 v[232:235], v230 offset:4096
	ds_read_b128 v[236:239], v230 offset:5120
	ds_read_b128 v[240:243], v230 offset:6144
	ds_read_b128 v[244:247], v230 offset:7168
	global_load_lds_dwordx4 v[96:97], off
	v_lshl_add_u64 v[96:97], s[44:45], 0, v[206:207]
	s_add_i32 m0, s35, 0xe000
	s_nop 0
	global_load_lds_dwordx4 v[96:97], off
	s_waitcnt vmcnt(8)
	s_waitcnt lgkmcnt(0)
	s_barrier
	s_setprio 1
	s_waitcnt lgkmcnt(0)
	v_mfma_f32_16x16x32_bf16 v[150:153], v[60:63], v[158:161], v[150:153]
	v_mfma_f32_16x16x32_bf16 v[130:133], v[68:71], v[158:161], v[130:133]
	v_mfma_f32_16x16x32_bf16 v[146:149], v[60:63], v[170:173], v[146:149]
	v_mfma_f32_16x16x32_bf16 v[138:141], v[68:71], v[170:173], v[138:141]
	v_mfma_f32_16x16x32_bf16 v[126:129], v[60:63], v[232:235], v[126:129]
	v_mfma_f32_16x16x32_bf16 v[118:121], v[68:71], v[232:235], v[118:121]
	v_mfma_f32_16x16x32_bf16 v[110:113], v[60:63], v[240:243], v[110:113]
	v_mfma_f32_16x16x32_bf16 v[96:99], v[68:71], v[240:243], v[98:101]
	v_mfma_f32_16x16x32_bf16 v[150:153], v[64:67], v[162:165], v[150:153]
	v_mfma_f32_16x16x32_bf16 v[130:133], v[72:75], v[162:165], v[130:133]
	v_mfma_f32_16x16x32_bf16 v[146:149], v[64:67], v[174:177], v[146:149]
	v_mfma_f32_16x16x32_bf16 v[138:141], v[72:75], v[174:177], v[138:141]
	v_mfma_f32_16x16x32_bf16 v[126:129], v[64:67], v[236:239], v[126:129]
	v_mfma_f32_16x16x32_bf16 v[118:121], v[72:75], v[236:239], v[118:121]
	v_mfma_f32_16x16x32_bf16 v[110:113], v[64:67], v[244:247], v[110:113]
	v_mfma_f32_16x16x32_bf16 v[96:99], v[72:75], v[244:247], v[96:99]
	s_setprio 0
	s_setprio 1
	v_mfma_f32_16x16x32_bf16 v[166:169], v[80:83], v[158:161], v[166:169]
	v_mfma_f32_16x16x32_bf16 v[154:157], v[88:91], v[158:161], v[154:157]
	v_mfma_f32_16x16x32_bf16 v[142:145], v[80:83], v[170:173], v[142:145]
	v_mfma_f32_16x16x32_bf16 v[134:137], v[88:91], v[170:173], v[134:137]
	v_mfma_f32_16x16x32_bf16 v[122:125], v[80:83], v[232:235], v[122:125]
	v_mfma_f32_16x16x32_bf16 v[114:117], v[88:91], v[232:235], v[114:117]
	v_mfma_f32_16x16x32_bf16 v[106:109], v[80:83], v[240:243], v[106:109]
	v_mfma_f32_16x16x32_bf16 v[100:103], v[88:91], v[240:243], v[102:105]
	v_mfma_f32_16x16x32_bf16 v[166:169], v[84:87], v[162:165], v[166:169]
	v_mfma_f32_16x16x32_bf16 v[154:157], v[92:95], v[162:165], v[154:157]
	v_mfma_f32_16x16x32_bf16 v[142:145], v[84:87], v[174:177], v[142:145]
	v_mfma_f32_16x16x32_bf16 v[134:137], v[92:95], v[174:177], v[134:137]
	v_mfma_f32_16x16x32_bf16 v[122:125], v[84:87], v[236:239], v[122:125]
	v_mfma_f32_16x16x32_bf16 v[114:117], v[92:95], v[236:239], v[114:117]
	v_mfma_f32_16x16x32_bf16 v[106:109], v[84:87], v[244:247], v[106:109]
	v_mfma_f32_16x16x32_bf16 v[102:105], v[92:95], v[244:247], v[100:103]
	s_setprio 0
	s_barrier
	s_add_i32 s40, s91, s26
	v_lshl_add_u64 v[208:209], s[62:63], 0, v[196:197]
	s_mov_b32 m0, s40
	ds_read_b128 v[158:161], v230 offset:16384
	ds_read_b128 v[162:165], v230 offset:17408
	ds_read_b128 v[170:173], v230 offset:18432
	ds_read_b128 v[174:177], v230 offset:19456
	ds_read_b128 v[232:235], v230 offset:20480
	ds_read_b128 v[236:239], v230 offset:21504
	ds_read_b128 v[240:243], v230 offset:22528
	ds_read_b128 v[244:247], v230 offset:23552
	global_load_lds_dwordx4 v[208:209], off
	s_add_i32 m0, s40, 0x2000
	s_add_u32 s40, s62, 0x40000
	v_lshl_add_u64 v[248:249], s[62:63], 0, v[200:201]
	s_addc_u32 s41, s63, 0
	s_add_i32 s54, s54, s26
	global_load_lds_dwordx4 v[248:249], off
	v_lshl_add_u64 v[100:101], s[40:41], 0, v[196:197]
	s_mov_b32 m0, s54
	v_lshl_add_u64 v[250:251], vcc, 0, v[194:195]
	global_load_lds_dwordx4 v[100:101], off
	v_lshl_add_u64 v[100:101], s[40:41], 0, v[200:201]
	s_add_i32 m0, s54, 0x2000
	v_lshl_add_u64 v[184:185], vcc, 0, v[198:199]
	global_load_lds_dwordx4 v[100:101], off
	s_mov_b32 m0, s35
	s_nop 0
	global_load_lds_dwordx4 v[250:251], off
	s_mov_b32 m0, s93
	s_nop 0
	global_load_lds_dwordx4 v[184:185], off
	s_waitcnt vmcnt(8)
	s_waitcnt lgkmcnt(0)
	s_barrier
	s_setprio 1
	s_waitcnt lgkmcnt(0)
	v_mfma_f32_16x16x32_bf16 v[52:55], v[60:63], v[158:161], v[52:55]
	v_mfma_f32_16x16x32_bf16 v[36:39], v[68:71], v[158:161], v[36:39]
	v_mfma_f32_16x16x32_bf16 v[48:51], v[60:63], v[170:173], v[48:51]
	v_mfma_f32_16x16x32_bf16 v[40:43], v[68:71], v[170:173], v[40:43]
	v_mfma_f32_16x16x32_bf16 v[28:31], v[60:63], v[232:235], v[28:31]
	v_mfma_f32_16x16x32_bf16 v[20:23], v[68:71], v[232:235], v[20:23]
	v_mfma_f32_16x16x32_bf16 v[12:15], v[60:63], v[240:243], v[12:15]
	v_mfma_f32_16x16x32_bf16 v[4:7], v[68:71], v[240:243], v[4:7]
	v_mfma_f32_16x16x32_bf16 v[52:55], v[64:67], v[162:165], v[52:55]
	v_mfma_f32_16x16x32_bf16 v[36:39], v[72:75], v[162:165], v[36:39]
	v_mfma_f32_16x16x32_bf16 v[48:51], v[64:67], v[174:177], v[48:51]
	v_mfma_f32_16x16x32_bf16 v[40:43], v[72:75], v[174:177], v[40:43]
	v_mfma_f32_16x16x32_bf16 v[28:31], v[64:67], v[236:239], v[28:31]
	v_mfma_f32_16x16x32_bf16 v[20:23], v[72:75], v[236:239], v[20:23]
	v_mfma_f32_16x16x32_bf16 v[12:15], v[64:67], v[244:247], v[12:15]
	v_mfma_f32_16x16x32_bf16 v[4:7], v[72:75], v[244:247], v[4:7]
	s_setprio 0
	s_setprio 1
	v_mfma_f32_16x16x32_bf16 v[56:59], v[88:91], v[158:161], v[56:59]
	v_mfma_f32_16x16x32_bf16 v[44:47], v[80:83], v[170:173], v[44:47]
	v_mfma_f32_16x16x32_bf16 v[32:35], v[88:91], v[170:173], v[32:35]
	v_mfma_f32_16x16x32_bf16 v[24:27], v[80:83], v[232:235], v[24:27]
	v_mfma_f32_16x16x32_bf16 v[16:19], v[88:91], v[232:235], v[16:19]
	v_mfma_f32_16x16x32_bf16 v[8:11], v[80:83], v[240:243], v[8:11]
	v_mfma_f32_16x16x32_bf16 v[0:3], v[88:91], v[240:243], v[0:3]
	v_mfma_f32_16x16x32_bf16 v[60:63], v[80:83], v[158:161], v[76:79]
	v_mfma_f32_16x16x32_bf16 v[56:59], v[92:95], v[162:165], v[56:59]
	v_mfma_f32_16x16x32_bf16 v[44:47], v[84:87], v[174:177], v[44:47]
	v_mfma_f32_16x16x32_bf16 v[32:35], v[92:95], v[174:177], v[32:35]
	v_mfma_f32_16x16x32_bf16 v[24:27], v[84:87], v[236:239], v[24:27]
	v_mfma_f32_16x16x32_bf16 v[16:19], v[92:95], v[236:239], v[16:19]
	v_mfma_f32_16x16x32_bf16 v[8:11], v[84:87], v[244:247], v[8:11]
	v_mfma_f32_16x16x32_bf16 v[0:3], v[92:95], v[244:247], v[0:3]
	v_mfma_f32_16x16x32_bf16 v[60:63], v[84:87], v[162:165], v[60:63]
	s_setprio 0
	s_barrier
	s_add_i32 s54, 0, 0x18000
	s_add_i32 s91, 0, 0x1c000
	v_add_u32_e32 v76, s54, v210
	v_add_u32_e32 v92, s91, v210
	ds_read_b128 v[64:67], v76
	ds_read_b128 v[68:71], v76 offset:1024
	ds_read_b128 v[72:75], v76 offset:2048
	ds_read_b128 v[76:79], v76 offset:3072
	ds_read_b128 v[80:83], v92
	ds_read_b128 v[84:87], v92 offset:1024
	ds_read_b128 v[88:91], v92 offset:2048
	ds_read_b128 v[92:95], v92 offset:3072
	s_add_u32 s40, vcc_lo, 0x40000
	s_addc_u32 s41, vcc_hi, 0
	s_mov_b32 m0, s33
	v_lshl_add_u64 v[100:101], s[40:41], 0, v[194:195]
	ds_read_b128 v[158:161], v230 offset:32768
	ds_read_b128 v[162:165], v230 offset:33792
	ds_read_b128 v[170:173], v230 offset:34816
	ds_read_b128 v[174:177], v230 offset:35840
	ds_read_b128 v[232:235], v230 offset:36864
	ds_read_b128 v[236:239], v230 offset:37888
	ds_read_b128 v[240:243], v230 offset:38912
	ds_read_b128 v[244:247], v230 offset:39936
	global_load_lds_dwordx4 v[100:101], off
	v_lshl_add_u64 v[100:101], s[40:41], 0, v[198:199]
	s_mov_b32 m0, s58
	s_nop 0
	global_load_lds_dwordx4 v[100:101], off
	s_waitcnt vmcnt(8)
	s_waitcnt lgkmcnt(0)
	s_barrier
	s_setprio 1
	s_waitcnt lgkmcnt(0)
	v_mfma_f32_16x16x32_bf16 v[150:153], v[64:67], v[158:161], v[150:153]
	v_mfma_f32_16x16x32_bf16 v[130:133], v[72:75], v[158:161], v[130:133]
	v_mfma_f32_16x16x32_bf16 v[146:149], v[64:67], v[170:173], v[146:149]
	v_mfma_f32_16x16x32_bf16 v[138:141], v[72:75], v[170:173], v[138:141]
	v_mfma_f32_16x16x32_bf16 v[126:129], v[64:67], v[232:235], v[126:129]
	v_mfma_f32_16x16x32_bf16 v[118:121], v[72:75], v[232:235], v[118:121]
	v_mfma_f32_16x16x32_bf16 v[110:113], v[64:67], v[240:243], v[110:113]
	v_mfma_f32_16x16x32_bf16 v[96:99], v[72:75], v[240:243], v[96:99]
	v_mfma_f32_16x16x32_bf16 v[150:153], v[68:71], v[162:165], v[150:153]
	v_mfma_f32_16x16x32_bf16 v[130:133], v[76:79], v[162:165], v[130:133]
	v_mfma_f32_16x16x32_bf16 v[146:149], v[68:71], v[174:177], v[146:149]
	v_mfma_f32_16x16x32_bf16 v[138:141], v[76:79], v[174:177], v[138:141]
	v_mfma_f32_16x16x32_bf16 v[126:129], v[68:71], v[236:239], v[126:129]
	v_mfma_f32_16x16x32_bf16 v[118:121], v[76:79], v[236:239], v[118:121]
	v_mfma_f32_16x16x32_bf16 v[110:113], v[68:71], v[244:247], v[110:113]
	v_mfma_f32_16x16x32_bf16 v[98:101], v[76:79], v[244:247], v[96:99]
	s_setprio 0
	s_setprio 1
	v_mfma_f32_16x16x32_bf16 v[166:169], v[80:83], v[158:161], v[166:169]
	v_mfma_f32_16x16x32_bf16 v[154:157], v[88:91], v[158:161], v[154:157]
	v_mfma_f32_16x16x32_bf16 v[142:145], v[80:83], v[170:173], v[142:145]
	v_mfma_f32_16x16x32_bf16 v[134:137], v[88:91], v[170:173], v[134:137]
	v_mfma_f32_16x16x32_bf16 v[122:125], v[80:83], v[232:235], v[122:125]
	v_mfma_f32_16x16x32_bf16 v[114:117], v[88:91], v[232:235], v[114:117]
	v_mfma_f32_16x16x32_bf16 v[106:109], v[80:83], v[240:243], v[106:109]
	v_mfma_f32_16x16x32_bf16 v[102:105], v[88:91], v[240:243], v[102:105]
	v_mfma_f32_16x16x32_bf16 v[166:169], v[84:87], v[162:165], v[166:169]
	v_mfma_f32_16x16x32_bf16 v[154:157], v[92:95], v[162:165], v[154:157]
	v_mfma_f32_16x16x32_bf16 v[142:145], v[84:87], v[174:177], v[142:145]
	v_mfma_f32_16x16x32_bf16 v[134:137], v[92:95], v[174:177], v[134:137]
	v_mfma_f32_16x16x32_bf16 v[122:125], v[84:87], v[236:239], v[122:125]
	v_mfma_f32_16x16x32_bf16 v[114:117], v[92:95], v[236:239], v[114:117]
	v_mfma_f32_16x16x32_bf16 v[106:109], v[84:87], v[244:247], v[106:109]
	v_mfma_f32_16x16x32_bf16 v[102:105], v[92:95], v[244:247], v[102:105]
	s_setprio 0
	s_barrier
	s_add_i32 s40, s54, s26
	v_lshl_add_u64 v[96:97], v[208:209], 0, s[28:29]
	s_mov_b32 m0, s40
	ds_read_b128 v[158:161], v230 offset:49152
	ds_read_b128 v[162:165], v230 offset:50176
	ds_read_b128 v[170:173], v230 offset:51200
	ds_read_b128 v[174:177], v230 offset:52224
	ds_read_b128 v[232:235], v230 offset:53248
	ds_read_b128 v[236:239], v230 offset:54272
	ds_read_b128 v[240:243], v230 offset:55296
	ds_read_b128 v[244:247], v230 offset:56320
	global_load_lds_dwordx4 v[96:97], off
	s_add_i32 m0, s40, 0x2000
	s_add_u32 s40, s62, 0x40080
	v_lshl_add_u64 v[96:97], v[248:249], 0, s[28:29]
	s_addc_u32 s41, s63, 0
	s_add_i32 s54, s91, s26
	global_load_lds_dwordx4 v[96:97], off
	v_lshl_add_u64 v[96:97], s[40:41], 0, v[196:197]
	s_mov_b32 m0, s54
	s_nop 0
	global_load_lds_dwordx4 v[96:97], off
	v_lshl_add_u64 v[96:97], s[40:41], 0, v[200:201]
	s_add_i32 m0, s54, 0x2000
	s_nop 0
	global_load_lds_dwordx4 v[96:97], off
	v_lshl_add_u64 v[96:97], v[250:251], 0, s[28:29]
	s_mov_b32 m0, s56
	s_nop 0
	global_load_lds_dwordx4 v[96:97], off
	v_lshl_add_u64 v[96:97], v[184:185], 0, s[28:29]
	s_mov_b32 m0, s57
	s_nop 0
	global_load_lds_dwordx4 v[96:97], off
	s_waitcnt vmcnt(8)
	s_waitcnt lgkmcnt(0)
	s_barrier
	s_setprio 1
	s_waitcnt lgkmcnt(0)
	v_mfma_f32_16x16x32_bf16 v[52:55], v[64:67], v[158:161], v[52:55]
	v_mfma_f32_16x16x32_bf16 v[36:39], v[72:75], v[158:161], v[36:39]
	v_mfma_f32_16x16x32_bf16 v[48:51], v[64:67], v[170:173], v[48:51]
	v_mfma_f32_16x16x32_bf16 v[40:43], v[72:75], v[170:173], v[40:43]
	v_mfma_f32_16x16x32_bf16 v[28:31], v[64:67], v[232:235], v[28:31]
	v_mfma_f32_16x16x32_bf16 v[20:23], v[72:75], v[232:235], v[20:23]
	v_mfma_f32_16x16x32_bf16 v[12:15], v[64:67], v[240:243], v[12:15]
	v_mfma_f32_16x16x32_bf16 v[4:7], v[72:75], v[240:243], v[4:7]
	v_mfma_f32_16x16x32_bf16 v[52:55], v[68:71], v[162:165], v[52:55]
	v_mfma_f32_16x16x32_bf16 v[36:39], v[76:79], v[162:165], v[36:39]
	v_mfma_f32_16x16x32_bf16 v[48:51], v[68:71], v[174:177], v[48:51]
	v_mfma_f32_16x16x32_bf16 v[40:43], v[76:79], v[174:177], v[40:43]
	v_mfma_f32_16x16x32_bf16 v[28:31], v[68:71], v[236:239], v[28:31]
	v_mfma_f32_16x16x32_bf16 v[20:23], v[76:79], v[236:239], v[20:23]
	v_mfma_f32_16x16x32_bf16 v[12:15], v[68:71], v[244:247], v[12:15]
	v_mfma_f32_16x16x32_bf16 v[4:7], v[76:79], v[244:247], v[4:7]
	s_setprio 0
	s_setprio 1
	v_mfma_f32_16x16x32_bf16 v[60:63], v[80:83], v[158:161], v[60:63]
	v_mfma_f32_16x16x32_bf16 v[56:59], v[88:91], v[158:161], v[56:59]
	v_mfma_f32_16x16x32_bf16 v[44:47], v[80:83], v[170:173], v[44:47]
	v_mfma_f32_16x16x32_bf16 v[32:35], v[88:91], v[170:173], v[32:35]
	v_mfma_f32_16x16x32_bf16 v[24:27], v[80:83], v[232:235], v[24:27]
	v_mfma_f32_16x16x32_bf16 v[16:19], v[88:91], v[232:235], v[16:19]
	v_mfma_f32_16x16x32_bf16 v[8:11], v[80:83], v[240:243], v[8:11]
	v_mfma_f32_16x16x32_bf16 v[0:3], v[88:91], v[240:243], v[0:3]
	v_mfma_f32_16x16x32_bf16 v[76:79], v[84:87], v[162:165], v[60:63]
	v_mfma_f32_16x16x32_bf16 v[56:59], v[92:95], v[162:165], v[56:59]
	v_mfma_f32_16x16x32_bf16 v[44:47], v[84:87], v[174:177], v[44:47]
	v_mfma_f32_16x16x32_bf16 v[32:35], v[92:95], v[174:177], v[32:35]
	v_mfma_f32_16x16x32_bf16 v[24:27], v[84:87], v[236:239], v[24:27]
	v_mfma_f32_16x16x32_bf16 v[16:19], v[92:95], v[236:239], v[16:19]
	v_mfma_f32_16x16x32_bf16 v[8:11], v[84:87], v[244:247], v[8:11]
	v_mfma_f32_16x16x32_bf16 v[0:3], v[92:95], v[244:247], v[0:3]
	s_setprio 0
	s_add_i32 s39, s39, 2
	s_add_u32 s44, s44, 0x100
	s_addc_u32 s45, s45, 0
	s_add_u32 s37, s37, 0x100
	s_addc_u32 s38, s38, 0
	s_cmp_gt_u32 s39, 13
	s_barrier
	s_cbranch_scc0 .LBB0_628
	s_and_b64 vcc, exec, s[52:53]
	s_cbranch_vccz .LBB0_631
	s_barrier

.LBB0_821:
	s_add_i32 vcc_lo, s60, 2
	s_add_u32 s44, s86, s88
	s_addc_u32 s45, s87, s89
	s_add_u32 s54, s84, s88
	s_addc_u32 vcc_hi, s85, s89
	s_add_i32 s56, 0, 0x10000
	s_cmp_eq_u32 s49, s60
	s_cselect_b32 s61, s41, s45
	s_cselect_b32 s60, s40, s44
	s_cselect_b32 s45, s83, vcc_hi
	s_cselect_b32 s44, s82, s54
	s_add_i32 s54, 0, 0x14000
	v_add_u32_e32 v152, s56, v138
	v_add_u32_e32 v161, s54, v138
	ds_read_b128 v[140:143], v152
	ds_read_b128 v[144:147], v152 offset:1024
	ds_read_b128 v[148:151], v152 offset:2048
	ds_read_b128 v[152:155], v152 offset:3072
	ds_read_b128 v[156:159], v161
	ds_read_b128 v[162:165], v161 offset:1024
	ds_read_b128 v[166:169], v161 offset:2048
	ds_read_b128 v[170:173], v161 offset:3072
	v_lshl_add_u64 v[184:185], s[86:87], 0, v[136:137]
	s_add_i32 m0, s63, 0xc000
	ds_read_b128 v[174:177], v139
	ds_read_b128 v[194:197], v139 offset:1024
	ds_read_b128 v[198:201], v139 offset:2048
	ds_read_b128 v[202:205], v139 offset:3072
	ds_read_b128 v[206:209], v139 offset:4096
	ds_read_b128 v[210:213], v139 offset:5120
	ds_read_b128 v[226:229], v139 offset:6144
	ds_read_b128 v[230:233], v139 offset:7168
	global_load_lds_dwordx4 v[184:185], off
	v_lshl_add_u64 v[184:185], s[86:87], 0, v[134:135]
	s_add_i32 m0, s63, 0xe000
	s_nop 0
	global_load_lds_dwordx4 v[184:185], off
	s_waitcnt vmcnt(8)
	s_waitcnt lgkmcnt(0)
	s_barrier
	s_setprio 1
	s_waitcnt lgkmcnt(0)
	v_mfma_f32_16x16x32_bf16 v[124:127], v[140:143], v[174:177], v[124:127]
	v_mfma_f32_16x16x32_bf16 v[120:123], v[148:151], v[174:177], v[120:123]
	v_mfma_f32_16x16x32_bf16 v[108:111], v[140:143], v[198:201], v[108:111]
	v_mfma_f32_16x16x32_bf16 v[104:107], v[148:151], v[198:201], v[104:107]
	v_mfma_f32_16x16x32_bf16 v[96:99], v[140:143], v[206:209], v[96:99]
	v_mfma_f32_16x16x32_bf16 v[88:91], v[148:151], v[206:209], v[88:91]
	v_mfma_f32_16x16x32_bf16 v[80:83], v[140:143], v[226:229], v[80:83]
	v_mfma_f32_16x16x32_bf16 v[72:75], v[148:151], v[226:229], v[72:75]
	v_mfma_f32_16x16x32_bf16 v[124:127], v[144:147], v[194:197], v[124:127]
	v_mfma_f32_16x16x32_bf16 v[120:123], v[152:155], v[194:197], v[120:123]
	v_mfma_f32_16x16x32_bf16 v[108:111], v[144:147], v[202:205], v[108:111]
	v_mfma_f32_16x16x32_bf16 v[104:107], v[152:155], v[202:205], v[104:107]
	v_mfma_f32_16x16x32_bf16 v[96:99], v[144:147], v[210:213], v[96:99]
	v_mfma_f32_16x16x32_bf16 v[88:91], v[152:155], v[210:213], v[88:91]
	v_mfma_f32_16x16x32_bf16 v[80:83], v[144:147], v[230:233], v[80:83]
	v_mfma_f32_16x16x32_bf16 v[72:75], v[152:155], v[230:233], v[72:75]
	s_setprio 0
	s_setprio 1
	v_mfma_f32_16x16x32_bf16 v[116:119], v[156:159], v[174:177], v[116:119]
	v_mfma_f32_16x16x32_bf16 v[112:115], v[166:169], v[174:177], v[112:115]
	v_mfma_f32_16x16x32_bf16 v[100:103], v[156:159], v[198:201], v[100:103]
	v_mfma_f32_16x16x32_bf16 v[92:95], v[166:169], v[198:201], v[92:95]
	v_mfma_f32_16x16x32_bf16 v[84:87], v[156:159], v[206:209], v[84:87]
	v_mfma_f32_16x16x32_bf16 v[76:79], v[166:169], v[206:209], v[76:79]
	v_mfma_f32_16x16x32_bf16 v[68:71], v[156:159], v[226:229], v[68:71]
	v_mfma_f32_16x16x32_bf16 v[60:63], v[166:169], v[226:229], v[60:63]
	v_mfma_f32_16x16x32_bf16 v[116:119], v[162:165], v[194:197], v[116:119]
	v_mfma_f32_16x16x32_bf16 v[112:115], v[170:173], v[194:197], v[112:115]
	v_mfma_f32_16x16x32_bf16 v[100:103], v[162:165], v[202:205], v[100:103]
	v_mfma_f32_16x16x32_bf16 v[92:95], v[170:173], v[202:205], v[92:95]
	v_mfma_f32_16x16x32_bf16 v[84:87], v[162:165], v[210:213], v[84:87]
	v_mfma_f32_16x16x32_bf16 v[76:79], v[170:173], v[210:213], v[76:79]
	v_mfma_f32_16x16x32_bf16 v[68:71], v[162:165], v[230:233], v[68:71]
	v_mfma_f32_16x16x32_bf16 v[60:63], v[170:173], v[230:233], v[60:63]
	s_setprio 0
	s_barrier
	s_add_i32 s56, s56, s58
	v_lshl_add_u64 v[184:185], s[44:45], 0, v[178:179]
	s_mov_b32 m0, s56
	ds_read_b128 v[174:177], v139 offset:16384
	ds_read_b128 v[194:197], v139 offset:17408
	ds_read_b128 v[198:201], v139 offset:18432
	ds_read_b128 v[202:205], v139 offset:19456
	ds_read_b128 v[206:209], v139 offset:20480
	ds_read_b128 v[210:213], v139 offset:21504
	ds_read_b128 v[226:229], v139 offset:22528
	ds_read_b128 v[230:233], v139 offset:23552
	global_load_lds_dwordx4 v[184:185], off
	s_add_i32 m0, s56, 0x2000
	v_lshl_add_u64 v[234:235], s[44:45], 0, v[128:129]
	s_add_u32 s44, s44, s23
	s_addc_u32 s45, s45, 0
	s_add_i32 s54, s54, s58
	global_load_lds_dwordx4 v[234:235], off
	v_lshl_add_u64 v[236:237], s[44:45], 0, v[178:179]
	s_mov_b32 m0, s54
	v_lshl_add_u64 v[238:239], s[44:45], 0, v[128:129]
	global_load_lds_dwordx4 v[236:237], off
	s_add_i32 m0, s54, 0x2000
	v_lshl_add_u64 v[240:241], s[60:61], 0, v[178:179]
	global_load_lds_dwordx4 v[238:239], off
	s_mov_b32 m0, s63
	v_lshl_add_u64 v[242:243], s[60:61], 0, v[128:129]
	global_load_lds_dwordx4 v[240:241], off
	s_mov_b32 m0, s91
	s_nop 0
	global_load_lds_dwordx4 v[242:243], off
	s_waitcnt vmcnt(8)
	s_waitcnt lgkmcnt(0)
	s_barrier
	s_setprio 1
	s_waitcnt lgkmcnt(0)
	v_mfma_f32_16x16x32_bf16 v[64:67], v[140:143], v[174:177], v[64:67]
	v_mfma_f32_16x16x32_bf16 v[56:59], v[148:151], v[174:177], v[56:59]
	v_mfma_f32_16x16x32_bf16 v[48:51], v[140:143], v[198:201], v[48:51]
	v_mfma_f32_16x16x32_bf16 v[40:43], v[148:151], v[198:201], v[40:43]
	v_mfma_f32_16x16x32_bf16 v[28:31], v[140:143], v[206:209], v[28:31]
	v_mfma_f32_16x16x32_bf16 v[24:27], v[148:151], v[206:209], v[24:27]
	v_mfma_f32_16x16x32_bf16 v[12:15], v[140:143], v[226:229], v[12:15]
	v_mfma_f32_16x16x32_bf16 v[8:11], v[148:151], v[226:229], v[8:11]
	v_mfma_f32_16x16x32_bf16 v[64:67], v[144:147], v[194:197], v[64:67]
	v_mfma_f32_16x16x32_bf16 v[56:59], v[152:155], v[194:197], v[56:59]
	v_mfma_f32_16x16x32_bf16 v[48:51], v[144:147], v[202:205], v[48:51]
	v_mfma_f32_16x16x32_bf16 v[40:43], v[152:155], v[202:205], v[40:43]
	v_mfma_f32_16x16x32_bf16 v[28:31], v[144:147], v[210:213], v[28:31]
	v_mfma_f32_16x16x32_bf16 v[24:27], v[152:155], v[210:213], v[24:27]
	v_mfma_f32_16x16x32_bf16 v[12:15], v[144:147], v[230:233], v[12:15]
	v_mfma_f32_16x16x32_bf16 v[8:11], v[152:155], v[230:233], v[8:11]
	s_setprio 0
	s_setprio 1
	v_mfma_f32_16x16x32_bf16 v[52:55], v[156:159], v[174:177], v[52:55]
	v_mfma_f32_16x16x32_bf16 v[44:47], v[166:169], v[174:177], v[44:47]
	v_mfma_f32_16x16x32_bf16 v[36:39], v[156:159], v[198:201], v[36:39]
	v_mfma_f32_16x16x32_bf16 v[32:35], v[166:169], v[198:201], v[32:35]
	v_mfma_f32_16x16x32_bf16 v[20:23], v[156:159], v[206:209], v[20:23]
	v_mfma_f32_16x16x32_bf16 v[16:19], v[166:169], v[206:209], v[16:19]
	v_mfma_f32_16x16x32_bf16 v[4:7], v[156:159], v[226:229], v[4:7]
	v_mfma_f32_16x16x32_bf16 v[0:3], v[166:169], v[226:229], v[0:3]
	v_mfma_f32_16x16x32_bf16 v[52:55], v[162:165], v[194:197], v[52:55]
	v_mfma_f32_16x16x32_bf16 v[44:47], v[170:173], v[194:197], v[44:47]
	v_mfma_f32_16x16x32_bf16 v[36:39], v[162:165], v[202:205], v[36:39]
	v_mfma_f32_16x16x32_bf16 v[32:35], v[170:173], v[202:205], v[32:35]
	v_mfma_f32_16x16x32_bf16 v[20:23], v[162:165], v[210:213], v[20:23]
	v_mfma_f32_16x16x32_bf16 v[16:19], v[170:173], v[210:213], v[16:19]
	v_mfma_f32_16x16x32_bf16 v[4:7], v[162:165], v[230:233], v[4:7]
	v_mfma_f32_16x16x32_bf16 v[0:3], v[170:173], v[230:233], v[0:3]
	s_setprio 0
	s_barrier
	s_add_i32 s54, 0, 0x18000
	s_add_i32 s56, 0, 0x1c000
	v_add_u32_e32 v152, s54, v138
	v_add_u32_e32 v161, s56, v138
	ds_read_b128 v[140:143], v152
	ds_read_b128 v[144:147], v152 offset:1024
	ds_read_b128 v[148:151], v152 offset:2048
	ds_read_b128 v[152:155], v152 offset:3072
	ds_read_b128 v[156:159], v161
	ds_read_b128 v[162:165], v161 offset:1024
	ds_read_b128 v[166:169], v161 offset:2048
	ds_read_b128 v[170:173], v161 offset:3072
	s_add_u32 s44, s60, s23
	s_addc_u32 s45, s61, 0
	s_mov_b32 m0, s92
	v_lshl_add_u64 v[244:245], s[44:45], 0, v[178:179]
	ds_read_b128 v[174:177], v139 offset:32768
	ds_read_b128 v[194:197], v139 offset:33792
	ds_read_b128 v[198:201], v139 offset:34816
	ds_read_b128 v[202:205], v139 offset:35840
	ds_read_b128 v[206:209], v139 offset:36864
	ds_read_b128 v[210:213], v139 offset:37888
	ds_read_b128 v[226:229], v139 offset:38912
	ds_read_b128 v[230:233], v139 offset:39936
	global_load_lds_dwordx4 v[244:245], off
	v_lshl_add_u64 v[244:245], s[44:45], 0, v[128:129]
	s_mov_b32 m0, s93
	s_nop 0
	global_load_lds_dwordx4 v[244:245], off
	s_waitcnt vmcnt(8)
	s_waitcnt lgkmcnt(0)
	s_barrier
	s_setprio 1
	s_waitcnt lgkmcnt(0)
	v_mfma_f32_16x16x32_bf16 v[124:127], v[140:143], v[174:177], v[124:127]
	v_mfma_f32_16x16x32_bf16 v[120:123], v[148:151], v[174:177], v[120:123]
	v_mfma_f32_16x16x32_bf16 v[108:111], v[140:143], v[198:201], v[108:111]
	v_mfma_f32_16x16x32_bf16 v[104:107], v[148:151], v[198:201], v[104:107]
	v_mfma_f32_16x16x32_bf16 v[96:99], v[140:143], v[206:209], v[96:99]
	v_mfma_f32_16x16x32_bf16 v[88:91], v[148:151], v[206:209], v[88:91]
	v_mfma_f32_16x16x32_bf16 v[80:83], v[140:143], v[226:229], v[80:83]
	v_mfma_f32_16x16x32_bf16 v[72:75], v[148:151], v[226:229], v[72:75]
	v_mfma_f32_16x16x32_bf16 v[124:127], v[144:147], v[194:197], v[124:127]
	v_mfma_f32_16x16x32_bf16 v[120:123], v[152:155], v[194:197], v[120:123]
	v_mfma_f32_16x16x32_bf16 v[108:111], v[144:147], v[202:205], v[108:111]
	v_mfma_f32_16x16x32_bf16 v[104:107], v[152:155], v[202:205], v[104:107]
	v_mfma_f32_16x16x32_bf16 v[96:99], v[144:147], v[210:213], v[96:99]
	v_mfma_f32_16x16x32_bf16 v[88:91], v[152:155], v[210:213], v[88:91]
	v_mfma_f32_16x16x32_bf16 v[80:83], v[144:147], v[230:233], v[80:83]
	v_mfma_f32_16x16x32_bf16 v[72:75], v[152:155], v[230:233], v[72:75]
	s_setprio 0
	s_setprio 1
	v_mfma_f32_16x16x32_bf16 v[116:119], v[156:159], v[174:177], v[116:119]
	v_mfma_f32_16x16x32_bf16 v[112:115], v[166:169], v[174:177], v[112:115]
	v_mfma_f32_16x16x32_bf16 v[100:103], v[156:159], v[198:201], v[100:103]
	v_mfma_f32_16x16x32_bf16 v[92:95], v[166:169], v[198:201], v[92:95]
	v_mfma_f32_16x16x32_bf16 v[84:87], v[156:159], v[206:209], v[84:87]
	v_mfma_f32_16x16x32_bf16 v[76:79], v[166:169], v[206:209], v[76:79]
	v_mfma_f32_16x16x32_bf16 v[68:71], v[156:159], v[226:229], v[68:71]
	v_mfma_f32_16x16x32_bf16 v[60:63], v[166:169], v[226:229], v[60:63]
	v_mfma_f32_16x16x32_bf16 v[116:119], v[162:165], v[194:197], v[116:119]
	v_mfma_f32_16x16x32_bf16 v[112:115], v[170:173], v[194:197], v[112:115]
	v_mfma_f32_16x16x32_bf16 v[100:103], v[162:165], v[202:205], v[100:103]
	v_mfma_f32_16x16x32_bf16 v[92:95], v[170:173], v[202:205], v[92:95]
	v_mfma_f32_16x16x32_bf16 v[84:87], v[162:165], v[210:213], v[84:87]
	v_mfma_f32_16x16x32_bf16 v[76:79], v[170:173], v[210:213], v[76:79]
	v_mfma_f32_16x16x32_bf16 v[68:71], v[162:165], v[230:233], v[68:71]
	v_mfma_f32_16x16x32_bf16 v[60:63], v[170:173], v[230:233], v[60:63]
	s_setprio 0
	s_barrier
	s_add_i32 s44, s54, s58
	v_lshl_add_u64 v[184:185], v[184:185], 0, s[28:29]
	s_mov_b32 m0, s44
	ds_read_b128 v[174:177], v139 offset:49152
	ds_read_b128 v[194:197], v139 offset:50176
	ds_read_b128 v[198:201], v139 offset:51200
	ds_read_b128 v[202:205], v139 offset:52224
	ds_read_b128 v[206:209], v139 offset:53248
	ds_read_b128 v[210:213], v139 offset:54272
	ds_read_b128 v[226:229], v139 offset:55296
	ds_read_b128 v[230:233], v139 offset:56320
	global_load_lds_dwordx4 v[184:185], off
	v_lshl_add_u64 v[184:185], v[234:235], 0, s[28:29]
	s_add_i32 m0, s44, 0x2000
	s_add_i32 s44, s56, s58
	global_load_lds_dwordx4 v[184:185], off
	v_lshl_add_u64 v[184:185], v[236:237], 0, s[28:29]
	s_mov_b32 m0, s44
	s_nop 0
	global_load_lds_dwordx4 v[184:185], off
	v_lshl_add_u64 v[184:185], v[238:239], 0, s[28:29]
	s_add_i32 m0, s44, 0x2000
	s_nop 0
	global_load_lds_dwordx4 v[184:185], off
	v_lshl_add_u64 v[184:185], v[240:241], 0, s[28:29]
	s_mov_b32 m0, s94
	s_nop 0
	global_load_lds_dwordx4 v[184:185], off
	v_lshl_add_u64 v[184:185], v[242:243], 0, s[28:29]
	s_mov_b32 m0, s95
	s_nop 0
	global_load_lds_dwordx4 v[184:185], off
	s_waitcnt vmcnt(8)
	s_waitcnt lgkmcnt(0)
	s_barrier
	s_setprio 1
	s_waitcnt lgkmcnt(0)
	v_mfma_f32_16x16x32_bf16 v[64:67], v[140:143], v[174:177], v[64:67]
	v_mfma_f32_16x16x32_bf16 v[56:59], v[148:151], v[174:177], v[56:59]
	v_mfma_f32_16x16x32_bf16 v[48:51], v[140:143], v[198:201], v[48:51]
	v_mfma_f32_16x16x32_bf16 v[40:43], v[148:151], v[198:201], v[40:43]
	v_mfma_f32_16x16x32_bf16 v[28:31], v[140:143], v[206:209], v[28:31]
	v_mfma_f32_16x16x32_bf16 v[24:27], v[148:151], v[206:209], v[24:27]
	v_mfma_f32_16x16x32_bf16 v[12:15], v[140:143], v[226:229], v[12:15]
	v_mfma_f32_16x16x32_bf16 v[8:11], v[148:151], v[226:229], v[8:11]
	v_mfma_f32_16x16x32_bf16 v[64:67], v[144:147], v[194:197], v[64:67]
	v_mfma_f32_16x16x32_bf16 v[56:59], v[152:155], v[194:197], v[56:59]
	v_mfma_f32_16x16x32_bf16 v[48:51], v[144:147], v[202:205], v[48:51]
	v_mfma_f32_16x16x32_bf16 v[40:43], v[152:155], v[202:205], v[40:43]
	v_mfma_f32_16x16x32_bf16 v[28:31], v[144:147], v[210:213], v[28:31]
	v_mfma_f32_16x16x32_bf16 v[24:27], v[152:155], v[210:213], v[24:27]
	v_mfma_f32_16x16x32_bf16 v[12:15], v[144:147], v[230:233], v[12:15]
	v_mfma_f32_16x16x32_bf16 v[8:11], v[152:155], v[230:233], v[8:11]
	s_setprio 0
	s_setprio 1
	v_mfma_f32_16x16x32_bf16 v[52:55], v[156:159], v[174:177], v[52:55]
	v_mfma_f32_16x16x32_bf16 v[44:47], v[166:169], v[174:177], v[44:47]
	v_mfma_f32_16x16x32_bf16 v[36:39], v[156:159], v[198:201], v[36:39]
	v_mfma_f32_16x16x32_bf16 v[32:35], v[166:169], v[198:201], v[32:35]
	v_mfma_f32_16x16x32_bf16 v[20:23], v[156:159], v[206:209], v[20:23]
	v_mfma_f32_16x16x32_bf16 v[16:19], v[166:169], v[206:209], v[16:19]
	v_mfma_f32_16x16x32_bf16 v[4:7], v[156:159], v[226:229], v[4:7]
	v_mfma_f32_16x16x32_bf16 v[0:3], v[166:169], v[226:229], v[0:3]
	v_mfma_f32_16x16x32_bf16 v[52:55], v[162:165], v[194:197], v[52:55]
	v_mfma_f32_16x16x32_bf16 v[44:47], v[170:173], v[194:197], v[44:47]
	v_mfma_f32_16x16x32_bf16 v[36:39], v[162:165], v[202:205], v[36:39]
	v_mfma_f32_16x16x32_bf16 v[32:35], v[170:173], v[202:205], v[32:35]
	v_mfma_f32_16x16x32_bf16 v[20:23], v[162:165], v[210:213], v[20:23]
	v_mfma_f32_16x16x32_bf16 v[16:19], v[170:173], v[210:213], v[16:19]
	v_mfma_f32_16x16x32_bf16 v[4:7], v[162:165], v[230:233], v[4:7]
	v_mfma_f32_16x16x32_bf16 v[0:3], v[170:173], v[230:233], v[0:3]
	s_setprio 0
	s_add_u32 s88, s88, 0x100
	s_addc_u32 s89, s89, 0
	v_lshl_add_u64 v[136:137], v[136:137], 0, s[30:31]
	v_lshl_add_u64 v[134:135], v[134:135], 0, s[30:31]
	s_cmp_ge_u32 vcc_lo, s48
	s_mov_b32 s60, vcc_lo
	s_barrier
	s_cbranch_scc0 .LBB0_821
	s_and_b64 vcc, exec, s[80:81]
	s_cbranch_vccz .LBB0_824
	s_barrier

.LBB0_1077:
	s_add_u32 s46, s44, 0xfffc0080
	s_addc_u32 s47, s45, -1
	s_add_i32 s63, 0, 0x10000
	s_cmp_eq_u32 s62, 12
	s_cselect_b32 s49, s23, s47
	s_cselect_b32 s48, s58, s46
	s_cselect_b32 s47, s21, s61
	s_cselect_b32 s46, s59, s60
	s_add_i32 s82, 0, 0x14000
	v_add_u32_e32 v154, s63, v143
	v_add_u32_e32 v170, s82, v143
	ds_read_b128 v[138:141], v154
	ds_read_b128 v[146:149], v154 offset:1024
	ds_read_b128 v[150:153], v154 offset:2048
	ds_read_b128 v[154:157], v154 offset:3072
	ds_read_b128 v[158:161], v170
	ds_read_b128 v[162:165], v170 offset:1024
	ds_read_b128 v[166:169], v170 offset:2048
	ds_read_b128 v[170:173], v170 offset:3072
	v_lshl_add_u64 v[234:235], s[44:45], 0, v[134:135]
	s_add_i32 m0, s34, 0xc000
	ds_read_b128 v[174:177], v145
	ds_read_b128 v[194:197], v145 offset:1024
	ds_read_b128 v[198:201], v145 offset:2048
	ds_read_b128 v[202:205], v145 offset:3072
	ds_read_b128 v[206:209], v145 offset:4096
	ds_read_b128 v[210:213], v145 offset:5120
	ds_read_b128 v[226:229], v145 offset:6144
	ds_read_b128 v[230:233], v145 offset:7168
	global_load_lds_dwordx4 v[234:235], off
	v_lshl_add_u64 v[234:235], s[44:45], 0, v[136:137]
	s_add_i32 m0, s34, 0xe000
	s_nop 0
	global_load_lds_dwordx4 v[234:235], off
	s_waitcnt vmcnt(8)
	s_waitcnt lgkmcnt(0)
	s_barrier
	s_setprio 1
	s_waitcnt lgkmcnt(0)
	v_mfma_f32_16x16x32_bf16 v[124:127], v[138:141], v[174:177], v[124:127]
	v_mfma_f32_16x16x32_bf16 v[120:123], v[150:153], v[174:177], v[120:123]
	v_mfma_f32_16x16x32_bf16 v[116:119], v[138:141], v[198:201], v[116:119]
	v_mfma_f32_16x16x32_bf16 v[108:111], v[150:153], v[198:201], v[108:111]
	v_mfma_f32_16x16x32_bf16 v[100:103], v[138:141], v[206:209], v[100:103]
	v_mfma_f32_16x16x32_bf16 v[92:95], v[150:153], v[206:209], v[92:95]
	v_mfma_f32_16x16x32_bf16 v[84:87], v[138:141], v[226:229], v[84:87]
	v_mfma_f32_16x16x32_bf16 v[76:79], v[150:153], v[226:229], v[76:79]
	v_mfma_f32_16x16x32_bf16 v[124:127], v[146:149], v[194:197], v[124:127]
	v_mfma_f32_16x16x32_bf16 v[120:123], v[154:157], v[194:197], v[120:123]
	v_mfma_f32_16x16x32_bf16 v[116:119], v[146:149], v[202:205], v[116:119]
	v_mfma_f32_16x16x32_bf16 v[108:111], v[154:157], v[202:205], v[108:111]
	v_mfma_f32_16x16x32_bf16 v[100:103], v[146:149], v[210:213], v[100:103]
	v_mfma_f32_16x16x32_bf16 v[92:95], v[154:157], v[210:213], v[92:95]
	v_mfma_f32_16x16x32_bf16 v[84:87], v[146:149], v[230:233], v[84:87]
	v_mfma_f32_16x16x32_bf16 v[76:79], v[154:157], v[230:233], v[76:79]
	s_setprio 0
	s_setprio 1
	v_mfma_f32_16x16x32_bf16 v[112:115], v[158:161], v[174:177], v[112:115]
	v_mfma_f32_16x16x32_bf16 v[104:107], v[166:169], v[174:177], v[104:107]
	v_mfma_f32_16x16x32_bf16 v[96:99], v[158:161], v[198:201], v[96:99]
	v_mfma_f32_16x16x32_bf16 v[88:91], v[166:169], v[198:201], v[88:91]
	v_mfma_f32_16x16x32_bf16 v[80:83], v[158:161], v[206:209], v[80:83]
	v_mfma_f32_16x16x32_bf16 v[72:75], v[166:169], v[206:209], v[72:75]
	v_mfma_f32_16x16x32_bf16 v[68:71], v[158:161], v[226:229], v[68:71]
	v_mfma_f32_16x16x32_bf16 v[64:67], v[166:169], v[226:229], v[64:67]
	v_mfma_f32_16x16x32_bf16 v[112:115], v[162:165], v[194:197], v[112:115]
	v_mfma_f32_16x16x32_bf16 v[104:107], v[170:173], v[194:197], v[104:107]
	v_mfma_f32_16x16x32_bf16 v[96:99], v[162:165], v[202:205], v[96:99]
	v_mfma_f32_16x16x32_bf16 v[88:91], v[170:173], v[202:205], v[88:91]
	v_mfma_f32_16x16x32_bf16 v[80:83], v[162:165], v[210:213], v[80:83]
	v_mfma_f32_16x16x32_bf16 v[72:75], v[170:173], v[210:213], v[72:75]
	v_mfma_f32_16x16x32_bf16 v[68:71], v[162:165], v[230:233], v[68:71]
	v_mfma_f32_16x16x32_bf16 v[64:67], v[170:173], v[230:233], v[64:67]
	s_setprio 0
	s_barrier
	s_add_i32 s63, s63, s26
	v_lshl_add_u64 v[234:235], s[46:47], 0, v[178:179]
	s_mov_b32 m0, s63
	ds_read_b128 v[174:177], v145 offset:16384
	ds_read_b128 v[194:197], v145 offset:17408
	ds_read_b128 v[198:201], v145 offset:18432
	ds_read_b128 v[202:205], v145 offset:19456
	ds_read_b128 v[206:209], v145 offset:20480
	ds_read_b128 v[210:213], v145 offset:21504
	ds_read_b128 v[226:229], v145 offset:22528
	ds_read_b128 v[230:233], v145 offset:23552
	global_load_lds_dwordx4 v[234:235], off
	s_add_i32 m0, s63, 0x2000
	s_add_u32 s80, s46, 0x40000
	v_lshl_add_u64 v[236:237], s[46:47], 0, v[128:129]
	s_addc_u32 s81, s47, 0
	s_add_i32 s63, s82, s26
	global_load_lds_dwordx4 v[236:237], off
	v_lshl_add_u64 v[238:239], s[80:81], 0, v[178:179]
	s_mov_b32 m0, s63
	v_lshl_add_u64 v[240:241], s[48:49], 0, v[130:131]
	global_load_lds_dwordx4 v[238:239], off
	v_lshl_add_u64 v[238:239], s[80:81], 0, v[128:129]
	s_add_i32 m0, s63, 0x2000
	s_nop 0
	global_load_lds_dwordx4 v[238:239], off
	v_lshl_add_u64 v[238:239], s[48:49], 0, v[132:133]
	s_mov_b32 m0, s34
	s_nop 0
	global_load_lds_dwordx4 v[238:239], off
	s_mov_b32 m0, s35
	s_nop 0
	global_load_lds_dwordx4 v[240:241], off
	s_waitcnt vmcnt(8)
	s_waitcnt lgkmcnt(0)
	s_barrier
	s_setprio 1
	s_waitcnt lgkmcnt(0)
	v_mfma_f32_16x16x32_bf16 v[60:63], v[138:141], v[174:177], v[60:63]
	v_mfma_f32_16x16x32_bf16 v[56:59], v[150:153], v[174:177], v[56:59]
	v_mfma_f32_16x16x32_bf16 v[52:55], v[138:141], v[198:201], v[52:55]
	v_mfma_f32_16x16x32_bf16 v[44:47], v[150:153], v[198:201], v[44:47]
	v_mfma_f32_16x16x32_bf16 v[36:39], v[138:141], v[206:209], v[36:39]
	v_mfma_f32_16x16x32_bf16 v[28:31], v[150:153], v[206:209], v[28:31]
	v_mfma_f32_16x16x32_bf16 v[20:23], v[138:141], v[226:229], v[20:23]
	v_mfma_f32_16x16x32_bf16 v[12:15], v[150:153], v[226:229], v[12:15]
	v_mfma_f32_16x16x32_bf16 v[60:63], v[146:149], v[194:197], v[60:63]
	v_mfma_f32_16x16x32_bf16 v[56:59], v[154:157], v[194:197], v[56:59]
	v_mfma_f32_16x16x32_bf16 v[52:55], v[146:149], v[202:205], v[52:55]
	v_mfma_f32_16x16x32_bf16 v[44:47], v[154:157], v[202:205], v[44:47]
	v_mfma_f32_16x16x32_bf16 v[36:39], v[146:149], v[210:213], v[36:39]
	v_mfma_f32_16x16x32_bf16 v[28:31], v[154:157], v[210:213], v[28:31]
	v_mfma_f32_16x16x32_bf16 v[20:23], v[146:149], v[230:233], v[20:23]
	v_mfma_f32_16x16x32_bf16 v[12:15], v[154:157], v[230:233], v[12:15]
	s_setprio 0
	s_setprio 1
	v_mfma_f32_16x16x32_bf16 v[48:51], v[158:161], v[174:177], v[48:51]
	v_mfma_f32_16x16x32_bf16 v[40:43], v[166:169], v[174:177], v[40:43]
	v_mfma_f32_16x16x32_bf16 v[32:35], v[158:161], v[198:201], v[32:35]
	v_mfma_f32_16x16x32_bf16 v[24:27], v[166:169], v[198:201], v[24:27]
	v_mfma_f32_16x16x32_bf16 v[16:19], v[158:161], v[206:209], v[16:19]
	v_mfma_f32_16x16x32_bf16 v[8:11], v[166:169], v[206:209], v[8:11]
	v_mfma_f32_16x16x32_bf16 v[4:7], v[158:161], v[226:229], v[4:7]
	v_mfma_f32_16x16x32_bf16 v[0:3], v[166:169], v[226:229], v[0:3]
	v_mfma_f32_16x16x32_bf16 v[48:51], v[162:165], v[194:197], v[48:51]
	v_mfma_f32_16x16x32_bf16 v[40:43], v[170:173], v[194:197], v[40:43]
	v_mfma_f32_16x16x32_bf16 v[32:35], v[162:165], v[202:205], v[32:35]
	v_mfma_f32_16x16x32_bf16 v[24:27], v[170:173], v[202:205], v[24:27]
	v_mfma_f32_16x16x32_bf16 v[16:19], v[162:165], v[210:213], v[16:19]
	v_mfma_f32_16x16x32_bf16 v[8:11], v[170:173], v[210:213], v[8:11]
	v_mfma_f32_16x16x32_bf16 v[4:7], v[162:165], v[230:233], v[4:7]
	v_mfma_f32_16x16x32_bf16 v[0:3], v[170:173], v[230:233], v[0:3]
	s_setprio 0
	s_barrier
	s_add_i32 s63, 0, 0x18000
	s_add_i32 s80, 0, 0x1c000
	v_add_u32_e32 v154, s63, v143
	v_add_u32_e32 v170, s80, v143
	ds_read_b128 v[138:141], v154
	ds_read_b128 v[146:149], v154 offset:1024
	ds_read_b128 v[150:153], v154 offset:2048
	ds_read_b128 v[154:157], v154 offset:3072
	ds_read_b128 v[158:161], v170
	ds_read_b128 v[162:165], v170 offset:1024
	ds_read_b128 v[166:169], v170 offset:2048
	ds_read_b128 v[170:173], v170 offset:3072
	s_add_u32 s48, s48, 0x40000
	s_addc_u32 s49, s49, 0
	s_mov_b32 m0, s50
	v_lshl_add_u64 v[242:243], s[48:49], 0, v[132:133]
	ds_read_b128 v[174:177], v145 offset:32768
	ds_read_b128 v[194:197], v145 offset:33792
	ds_read_b128 v[198:201], v145 offset:34816
	ds_read_b128 v[202:205], v145 offset:35840
	ds_read_b128 v[206:209], v145 offset:36864
	ds_read_b128 v[210:213], v145 offset:37888
	ds_read_b128 v[226:229], v145 offset:38912
	ds_read_b128 v[230:233], v145 offset:39936
	global_load_lds_dwordx4 v[242:243], off
	v_lshl_add_u64 v[242:243], s[48:49], 0, v[130:131]
	s_mov_b32 m0, s51
	s_nop 0
	global_load_lds_dwordx4 v[242:243], off
	s_waitcnt vmcnt(8)
	s_waitcnt lgkmcnt(0)
	s_barrier
	s_setprio 1
	s_waitcnt lgkmcnt(0)
	v_mfma_f32_16x16x32_bf16 v[124:127], v[138:141], v[174:177], v[124:127]
	v_mfma_f32_16x16x32_bf16 v[120:123], v[150:153], v[174:177], v[120:123]
	v_mfma_f32_16x16x32_bf16 v[116:119], v[138:141], v[198:201], v[116:119]
	v_mfma_f32_16x16x32_bf16 v[108:111], v[150:153], v[198:201], v[108:111]
	v_mfma_f32_16x16x32_bf16 v[100:103], v[138:141], v[206:209], v[100:103]
	v_mfma_f32_16x16x32_bf16 v[92:95], v[150:153], v[206:209], v[92:95]
	v_mfma_f32_16x16x32_bf16 v[84:87], v[138:141], v[226:229], v[84:87]
	v_mfma_f32_16x16x32_bf16 v[76:79], v[150:153], v[226:229], v[76:79]
	v_mfma_f32_16x16x32_bf16 v[124:127], v[146:149], v[194:197], v[124:127]
	v_mfma_f32_16x16x32_bf16 v[120:123], v[154:157], v[194:197], v[120:123]
	v_mfma_f32_16x16x32_bf16 v[116:119], v[146:149], v[202:205], v[116:119]
	v_mfma_f32_16x16x32_bf16 v[108:111], v[154:157], v[202:205], v[108:111]
	v_mfma_f32_16x16x32_bf16 v[100:103], v[146:149], v[210:213], v[100:103]
	v_mfma_f32_16x16x32_bf16 v[92:95], v[154:157], v[210:213], v[92:95]
	v_mfma_f32_16x16x32_bf16 v[84:87], v[146:149], v[230:233], v[84:87]
	v_mfma_f32_16x16x32_bf16 v[76:79], v[154:157], v[230:233], v[76:79]
	s_setprio 0
	s_setprio 1
	v_mfma_f32_16x16x32_bf16 v[112:115], v[158:161], v[174:177], v[112:115]
	v_mfma_f32_16x16x32_bf16 v[104:107], v[166:169], v[174:177], v[104:107]
	v_mfma_f32_16x16x32_bf16 v[96:99], v[158:161], v[198:201], v[96:99]
	v_mfma_f32_16x16x32_bf16 v[88:91], v[166:169], v[198:201], v[88:91]
	v_mfma_f32_16x16x32_bf16 v[80:83], v[158:161], v[206:209], v[80:83]
	v_mfma_f32_16x16x32_bf16 v[72:75], v[166:169], v[206:209], v[72:75]
	v_mfma_f32_16x16x32_bf16 v[68:71], v[158:161], v[226:229], v[68:71]
	v_mfma_f32_16x16x32_bf16 v[64:67], v[166:169], v[226:229], v[64:67]
	v_mfma_f32_16x16x32_bf16 v[112:115], v[162:165], v[194:197], v[112:115]
	v_mfma_f32_16x16x32_bf16 v[104:107], v[170:173], v[194:197], v[104:107]
	v_mfma_f32_16x16x32_bf16 v[96:99], v[162:165], v[202:205], v[96:99]
	v_mfma_f32_16x16x32_bf16 v[88:91], v[170:173], v[202:205], v[88:91]
	v_mfma_f32_16x16x32_bf16 v[80:83], v[162:165], v[210:213], v[80:83]
	v_mfma_f32_16x16x32_bf16 v[72:75], v[170:173], v[210:213], v[72:75]
	v_mfma_f32_16x16x32_bf16 v[68:71], v[162:165], v[230:233], v[68:71]
	v_mfma_f32_16x16x32_bf16 v[64:67], v[170:173], v[230:233], v[64:67]
	s_setprio 0
	s_barrier
	s_add_i32 s48, s63, s26
	v_lshl_add_u64 v[234:235], v[234:235], 0, s[28:29]
	s_mov_b32 m0, s48
	ds_read_b128 v[174:177], v145 offset:49152
	ds_read_b128 v[194:197], v145 offset:50176
	ds_read_b128 v[198:201], v145 offset:51200
	ds_read_b128 v[202:205], v145 offset:52224
	ds_read_b128 v[206:209], v145 offset:53248
	ds_read_b128 v[210:213], v145 offset:54272
	ds_read_b128 v[226:229], v145 offset:55296
	ds_read_b128 v[230:233], v145 offset:56320
	global_load_lds_dwordx4 v[234:235], off
	s_add_i32 m0, s48, 0x2000
	s_add_u32 s46, s46, 0x40080
	v_lshl_add_u64 v[234:235], v[236:237], 0, s[28:29]
	s_addc_u32 s47, s47, 0
	s_add_i32 s48, s80, s26
	global_load_lds_dwordx4 v[234:235], off
	v_lshl_add_u64 v[234:235], s[46:47], 0, v[178:179]
	s_mov_b32 m0, s48
	s_nop 0
	global_load_lds_dwordx4 v[234:235], off
	v_lshl_add_u64 v[234:235], s[46:47], 0, v[128:129]
	s_add_i32 m0, s48, 0x2000
	s_nop 0
	global_load_lds_dwordx4 v[234:235], off
	v_lshl_add_u64 v[234:235], v[238:239], 0, s[28:29]
	s_mov_b32 m0, s52
	s_nop 0
	global_load_lds_dwordx4 v[234:235], off
	v_lshl_add_u64 v[234:235], v[240:241], 0, s[28:29]
	s_mov_b32 m0, s53
	s_nop 0
	global_load_lds_dwordx4 v[234:235], off
	s_waitcnt vmcnt(8)
	s_waitcnt lgkmcnt(0)
	s_barrier
	s_setprio 1
	s_waitcnt lgkmcnt(0)
	v_mfma_f32_16x16x32_bf16 v[60:63], v[138:141], v[174:177], v[60:63]
	v_mfma_f32_16x16x32_bf16 v[56:59], v[150:153], v[174:177], v[56:59]
	v_mfma_f32_16x16x32_bf16 v[52:55], v[138:141], v[198:201], v[52:55]
	v_mfma_f32_16x16x32_bf16 v[44:47], v[150:153], v[198:201], v[44:47]
	v_mfma_f32_16x16x32_bf16 v[36:39], v[138:141], v[206:209], v[36:39]
	v_mfma_f32_16x16x32_bf16 v[28:31], v[150:153], v[206:209], v[28:31]
	v_mfma_f32_16x16x32_bf16 v[20:23], v[138:141], v[226:229], v[20:23]
	v_mfma_f32_16x16x32_bf16 v[12:15], v[150:153], v[226:229], v[12:15]
	v_mfma_f32_16x16x32_bf16 v[60:63], v[146:149], v[194:197], v[60:63]
	v_mfma_f32_16x16x32_bf16 v[56:59], v[154:157], v[194:197], v[56:59]
	v_mfma_f32_16x16x32_bf16 v[52:55], v[146:149], v[202:205], v[52:55]
	v_mfma_f32_16x16x32_bf16 v[44:47], v[154:157], v[202:205], v[44:47]
	v_mfma_f32_16x16x32_bf16 v[36:39], v[146:149], v[210:213], v[36:39]
	v_mfma_f32_16x16x32_bf16 v[28:31], v[154:157], v[210:213], v[28:31]
	v_mfma_f32_16x16x32_bf16 v[20:23], v[146:149], v[230:233], v[20:23]
	v_mfma_f32_16x16x32_bf16 v[12:15], v[154:157], v[230:233], v[12:15]
	s_setprio 0
	s_setprio 1
	v_mfma_f32_16x16x32_bf16 v[48:51], v[158:161], v[174:177], v[48:51]
	v_mfma_f32_16x16x32_bf16 v[40:43], v[166:169], v[174:177], v[40:43]
	v_mfma_f32_16x16x32_bf16 v[32:35], v[158:161], v[198:201], v[32:35]
	v_mfma_f32_16x16x32_bf16 v[24:27], v[166:169], v[198:201], v[24:27]
	v_mfma_f32_16x16x32_bf16 v[16:19], v[158:161], v[206:209], v[16:19]
	v_mfma_f32_16x16x32_bf16 v[8:11], v[166:169], v[206:209], v[8:11]
	v_mfma_f32_16x16x32_bf16 v[4:7], v[158:161], v[226:229], v[4:7]
	v_mfma_f32_16x16x32_bf16 v[0:3], v[166:169], v[226:229], v[0:3]
	v_mfma_f32_16x16x32_bf16 v[48:51], v[162:165], v[194:197], v[48:51]
	v_mfma_f32_16x16x32_bf16 v[40:43], v[170:173], v[194:197], v[40:43]
	v_mfma_f32_16x16x32_bf16 v[32:35], v[162:165], v[202:205], v[32:35]
	v_mfma_f32_16x16x32_bf16 v[24:27], v[170:173], v[202:205], v[24:27]
	v_mfma_f32_16x16x32_bf16 v[16:19], v[162:165], v[210:213], v[16:19]
	v_mfma_f32_16x16x32_bf16 v[8:11], v[170:173], v[210:213], v[8:11]
	v_mfma_f32_16x16x32_bf16 v[4:7], v[162:165], v[230:233], v[4:7]
	v_mfma_f32_16x16x32_bf16 v[0:3], v[170:173], v[230:233], v[0:3]
	s_setprio 0
	s_add_i32 s62, s62, 2
	s_add_u32 s44, s44, 0x100
	s_addc_u32 s45, s45, 0
	s_add_u32 s60, s60, 0x100
	s_addc_u32 s61, s61, 0
	s_cmp_gt_u32 s62, 13
	s_barrier
	s_cbranch_scc0 .LBB0_1077
	s_and_b64 vcc, exec, s[2:3]
	s_cbranch_vccz .LBB0_1080
	s_barrier
